# v3 + phase 9 tile order reversed (reads most recently written G tiles first: LIFO reuse of the infinity cache)
# speedup vs baseline: 1.0180x; 1.0074x over previous
; template <class Epi, class Sched, bool SP2 = PG8_SP2>
; __device__ __forceinline__ void gemm_phase(LAS unsigned char* lds, const Gemm g, const Sched& S, const Epi& E) {
;     const int tid = threadIdx.x, wid = __builtin_amdgcn_readfirstlane(tid >> 6), lane = tid & 63, wr = wid >> 2, wc = wid & 3, fr = lane & 15, fq = lane >> 4;
;     const int K = g.K, nt = K / BK, lda = g.lda;
;     unsigned voffA[2], voffB[2];
; #pragma unroll
;     for (int i = 0; i < 2; ++i) { int R, C; stage_rc(tid * 16 + i * 8192, R, C); const int Rb = Epi::PERM ? ((R & ~31) + perm32(R & 31)) : R;
;         voffA[i] = (unsigned)(R * lda + C) * 2u; voffB[i] = (unsigned)(Rb * K + C) * 2u; }
;     const size_t kstep = (size_t)(BK * 2);
;     const size_t hstepA = (size_t)HALF * lda * 2, hstepB = (size_t)HALF * K * 2;
;     const size_t tstepA = 2 * hstepA, tstepB = 2 * hstepB;
;     const unsigned ldsw = (unsigned)wid * 1024u;
;     const int aoff = lds_byte(wr * 64 + fr, fq * 8), boff = lds_byte(wc * 32 + fr, fq * 8);
;     ...
;     Unit cur, nxt; int ui = 0;
;     if (!S.next(0, cur)) return;
;     f32x4 acc[2][2][4][2];
; #pragma unroll
;     for (int a = 0; a < 2; ++a)
; #pragma unroll
;         for (int b = 0; b < 2; ++b)
; #pragma unroll
;             for (int m = 0; m < 4; ++m)
; #pragma unroll
;                 for (int n = 0; n < 2; ++n) acc[a][b][m][n] = (f32x4){0.f, 0.f, 0.f, 0.f};
;     bf16x8 At[4][2], B0[2][2], B1[2][2];
;     const char* cA = (const char*)g.A + (size_t)cur.pm * tstepA; const char* cB = (const char*)g.Bt + (size_t)cur.pn * tstepB;
;     if constexpr (SP2) {
;     PG8_STAGE(PG8_SB(0, 0), cB, voffB); PG8_STAGE(PG8_SB(0, 1), cB + hstepB, voffB); PG8_STAGE(PG8_SA(0, 0), cA, voffA); PG8_STAGE(PG8_SA(0, 1), cA + hstepA, voffA);
;     if (wr == 1) PG8_BAR;
;     PG8_WAIT_V(2); PG8_BAR;
;     PG8_STAGE(PG8_SB(1, 0), cB + kstep, voffB); PG8_STAGE(PG8_SA(1, 0), cA + kstep, voffA); PG8_STAGE(PG8_SB(1, 1), cB + hstepB + kstep, voffB);
;     PG8_WAIT_V(6); PG8_BAR;
;     } else {
;     PG8_STAGE(PG8_SB(0, 0), cB, voffB); PG8_STAGE(PG8_SA(0, 0), cA, voffA); PG8_STAGE(PG8_SB(0, 1), cB + hstepB, voffB); PG8_STAGE(PG8_SA(0, 1), cA + hstepA, voffA);
;     if (wr == 1) PG8_BAR;
;     PG8_WAIT_V(4); PG8_BAR;
;     PG8_STAGE(PG8_SB(1, 0), cB + kstep, voffB); PG8_STAGE(PG8_SA(1, 0), cA + kstep, voffA); PG8_STAGE(PG8_SB(1, 1), cB + hstepB + kstep, voffB);
;     PG8_WAIT_V(6); PG8_BAR;
.LBB0_993:
	v_readlane_b32 s2, v240, 5
	v_readlane_b32 s3, v240, 6
	s_cmp_lt_i32 s2, 10
	s_cselect_b64 s[2:3], -1, 0
	s_waitcnt lgkmcnt(0)
	s_and_b64 s[10:11], s[2:3], s[0:1]
	s_andn2_b64 vcc, exec, s[10:11]
	s_cbranch_vccnz .LBB0_1014
	s_cmpk_gt_i32 s88, 0xaff
	v_readfirstlane_b32 s2, v222
	s_cbranch_scc1 .LBB0_1014
	s_load_dwordx2 s[4:5], s[78:79], 0xc0
	v_lshrrev_b32_e32 v0, 5, v222
	v_lshrrev_b32_e32 v2, 1, v222
	v_and_b32_e32 v0, 4, v0
	v_bfe_u32 v1, v222, 2, 2
	v_and_b32_e32 v11, 24, v2
	v_or3_b32 v0, v0, v1, v11
	v_lshlrev_b32_e32 v1, 4, v222
	v_add_u32_e32 v8, 0x2000, v1
	v_lshrrev_b32_e32 v2, 7, v8
	s_movk_i32 s0, 0xe0
	v_and_b32_e32 v4, 32, v222
	s_waitcnt lgkmcnt(0)
	s_add_u32 s33, s4, 0x8000000
	v_and_or_b32 v3, v2, s0, v0
	v_bitop3_b32 v9, v1, v4, 48 bitop3:0x6c
	v_and_b32_e32 v10, 64, v222
	v_bfe_u32 v12, v222, 2, 4
	s_movk_i32 s0, 0xf0
	s_addc_u32 s44, s5, 0
	v_or_b32_e32 v1, v9, v10
	v_and_or_b32 v2, v2, s0, v12
	s_add_u32 s45, s4, 0x3000000
	v_lshl_or_b32 v188, v2, 12, v1
	v_lshrrev_b32_e32 v2, 3, v222
	s_movk_i32 s0, 0x60
	s_addc_u32 s46, s5, 0
	v_and_or_b32 v0, v2, s0, v0
	s_movk_i32 s0, 0x70
	s_ashr_i32 s48, s88, 31
	v_lshl_or_b32 v190, v0, 12, v1
	v_and_or_b32 v0, v2, s0, v12
	s_lshr_b32 s0, s48, 29
	s_add_i32 s0, s88, s0
	s_lshr_b32 s24, s2, 6
	s_ashr_i32 s1, s0, 3
	s_and_b32 s0, s0, -8
	s_lshr_b32 s3, s2, 8
	s_lshl_b32 s47, s24, 10
	s_sub_i32 s0, s88, s0
	s_cmp_lt_i32 s0, 0
	s_movk_i32 s49, 0x161
	s_cselect_b32 s6, s49, 0x160
	s_mul_i32 s0, s6, s0
	s_add_i32 s0, s0, s1
	s_addk_i32 s0, 0x140
	s_mul_hi_i32 s1, s0, 0x2e8ba2e9
	s_lshr_b32 s6, s1, 31
	s_ashr_i32 s1, s1, 5
	s_add_i32 s1, s1, s6
	s_lshl_b32 s6, s1, 3
	s_mulk_i32 s1, 0xb0
	s_sub_i32 s0, s0, s1
	s_sext_i32_i16 s1, s0
	s_bfe_u32 s1, s1, 0x3001c
	s_add_i32 s1, s0, s1
	s_sext_i32_i16 s7, s1
	s_and_b32 s1, s1, 0xfff8
	s_sub_i32 s0, s0, s1
	s_sext_i32_i16 s0, s0
	s_lshr_b32 s26, s7, 3
	s_add_i32 s6, s6, s0
	s_ashr_i32 s7, s6, 31
	s_bfe_i64 s[8:9], s[26:27], 0x100000
	s_lshl_b64 s[0:1], s[6:7], 20
	s_lshl_b64 s[8:9], s[8:9], 20
	s_add_u32 s8, s45, s8
	s_addc_u32 s9, s46, s9
	s_add_i32 s50, s47, 0
	s_add_i32 m0, s50, 0x10000
	v_lshl_or_b32 v186, v3, 12, v1
	global_load_lds_dwordx4 v190, s[8:9]
	s_add_i32 m0, s50, 0x12000
	s_add_u32 s12, s8, 0x80000
	global_load_lds_dwordx4 v186, s[8:9]
	s_addc_u32 s13, s9, 0
	s_add_i32 m0, s50, 0x14000
	v_lshl_or_b32 v192, v0, 12, v1
	global_load_lds_dwordx4 v190, s[12:13]
	s_add_i32 m0, s50, 0x16000
	s_add_u32 s0, s33, s0
	s_addc_u32 s1, s44, s1
	s_add_i32 s51, s50, 0x2000
	global_load_lds_dwordx4 v186, s[12:13]
	s_mov_b32 m0, s50
	s_add_u32 s12, s0, 0x80000
	global_load_lds_dwordx4 v192, s[0:1]
	s_mov_b32 m0, s51
	s_addc_u32 s13, s1, 0
	s_add_i32 s52, s50, 0x4000
	global_load_lds_dwordx4 v188, s[0:1]
	s_mov_b32 m0, s52
	s_add_i32 s53, s50, 0x6000
	global_load_lds_dwordx4 v192, s[12:13]
	s_mov_b32 m0, s53
	v_mov_b32_e32 v191, 0
	global_load_lds_dwordx4 v188, s[12:13]
	s_load_dwordx4 s[12:15], s[78:79], 0xa0
	v_mov_b32_e32 v187, v191
	v_mov_b32_e32 v193, v191
	v_mov_b32_e32 v189, v191
	s_cmp_eq_u32 s3, 1
	s_mov_b32 s54, 0
	v_lshl_add_u64 v[6:7], s[8:9], 0, v[190:191]
	v_lshl_add_u64 v[4:5], s[8:9], 0, v[186:187]
	v_lshl_add_u64 v[0:1], s[0:1], 0, v[192:193]
	s_cselect_b64 s[16:17], -1, 0
	s_cmp_lg_u32 s3, 1
	v_lshl_add_u64 v[2:3], s[0:1], 0, v[188:189]
	s_cbranch_scc1 .LBB0_997
	s_barrier

;     __device__ bool next(int i, Unit& u) const {
;         const long L = (long)i * G + c; if (L >= nwg) return false;
;         int wgid = (int)L; { const int q = nwg / NXCD, r = nwg % NXCD, xcd = wgid % NXCD, off = wgid / NXCD; wgid = (xcd < r ? xcd * (q + 1) : r * (q + 1) + (xcd - r) * q) + off; }
;         const int nig = WGM * nN, gid = wgid / nig, fm = gid * WGM, gsz = (nM - fm) < WGM ? (nM - fm) : WGM;
;         u.pm = fm + ((wgid % nig) % gsz); u.pn = (wgid % nig) / gsz; return true;
;     }
; template <class Epi, class Sched, bool SP2 = PG8_SP2>
; __device__ __forceinline__ void gemm_phase(LAS unsigned char* lds, const Gemm g, const Sched& S, const Epi& E) {
;     ...
;         const bool has_next = S.next(ui + 1, nxt);
;         const char* nA = has_next ? (const char*)g.A + (size_t)nxt.pm * tstepA : cA; const char* nB = has_next ? (const char*)g.Bt + (size_t)nxt.pn * tstepB : cB;
.LBB0_1000:
	s_add_i32 s54, s54, 1
	s_sub_i32 s2, 10, s54
	s_mul_i32 s3, s2, s86
	s_add_i32 s36, s3, s88
	s_cmp_lt_i32 s2, 0
	s_cselect_b32 s36, 0xb00, s36
	s_mov_b32 s37, 0
	v_cmp_gt_i64_e32 vcc, s[36:37], v[200:201]
	v_cmp_lt_i64_e64 s[4:5], s[36:37], v[198:199]
	s_cbranch_vccnz .LBB0_1002
	s_ashr_i32 s2, s36, 31
	s_lshr_b32 s2, s2, 29
	s_add_i32 s2, s36, s2
	s_ashr_i32 s3, s2, 3
	s_and_b32 s2, s2, -8
	s_sub_i32 s2, s36, s2
	s_cmp_lt_i32 s2, 0
	s_cselect_b32 s34, s49, 0x160
	s_mul_i32 s2, s34, s2
	s_add_i32 s2, s2, s3
	s_mul_hi_i32 s3, s2, 0x2e8ba2e9
	s_lshr_b32 s34, s3, 31
	s_ashr_i32 s3, s3, 5
	s_add_i32 s3, s3, s34
	s_lshl_b32 s35, s3, 3
	s_sub_i32 s34, 0x80, s35
	s_min_i32 s36, s34, 8
	s_abs_i32 s34, s36
	v_cvt_f32_u32_e32 v0, s34
	s_sub_i32 s38, 0, s34
	s_mulk_i32 s3, 0xb0
	s_sub_i32 s2, s2, s3
	v_rcp_iflag_f32_e32 v0, v0
	s_abs_i32 s3, s2
	s_xor_b32 s37, s2, s36
	s_ashr_i32 s37, s37, 31
	v_mul_f32_e32 v0, 0x4f7ffffe, v0
	v_cvt_u32_f32_e32 v0, v0
	s_nop 0
	v_readfirstlane_b32 s39, v0
	s_mul_i32 s38, s38, s39
	s_mul_hi_u32 s38, s39, s38
	s_add_i32 s39, s39, s38
	s_mul_hi_u32 s38, s3, s39
	s_mul_i32 s39, s38, s34
	s_sub_i32 s3, s3, s39
	s_add_i32 s40, s38, 1
	s_sub_i32 s39, s3, s34
	s_cmp_ge_u32 s3, s34
	s_cselect_b32 s38, s40, s38
	s_cselect_b32 s3, s39, s3
	s_add_i32 s39, s38, 1
	s_cmp_ge_u32 s3, s34
	s_cselect_b32 s3, s39, s38
	s_xor_b32 s3, s3, s37
	s_sub_i32 s34, s3, s37
	s_mul_i32 s3, s34, s36
	s_sub_i32 s2, s2, s3
	s_add_i32 s38, s2, s35
